# softmax row-max tree split into two independent v_max3 chains inside the last P.V MFMA gaps (bit-identical), paired re-test
# speedup vs baseline: 1.0026x; 1.0026x over previous
; #define SBAR() __builtin_amdgcn_sched_barrier(0)
; #define SLOAD(i, k0) do { sr_[i].vs0 = *reinterpret_cast<const bf16x8*>(&Vh[(size_t)((k0) + sr) * 128 + sc]); sr_[i].vs1 = *reinterpret_cast<const bf16x8*>(&Vh[(size_t)((k0) + 32 + sr) * 128 + sc]); \
;     sr_[i].ks0 = *reinterpret_cast<const bf16x8*>(&Kh[(size_t)((k0) + kr) * 64 + kc]); } while (0)
; DEV void finishSM(f32x16& p0, f32x16& p1, float alpha, float& l_reg, bf16x8& pa0, bf16x8& pa1, bf16x8& pa2, bf16x8& pa3) {
; #pragma unroll
;   for (int r = 0; r < 16; ++r) p1[r] = __builtin_amdgcn_exp2f(p1[r]);
;   float ps = 0;
; #pragma unroll
;   for (int r = 0; r < 16; ++r) ps += p0[r];
; #pragma unroll
;   for (int r = 0; r < 16; ++r) ps += p1[r];
;   { auto rr = __builtin_amdgcn_permlane32_swap(__float_as_uint(ps), __float_as_uint(ps), false, false);
;     ps = __uint_as_float(rr[0]) + __uint_as_float(rr[1]); }
;   l_reg = l_reg * alpha + ps;
;     ...
;   PK4(p0, 0, pa0); PK4(p0, 8, pa1); PK4(p1, 0, pa2); PK4(p1, 8, pa3);
; DEV void attn_pass(const u16* __restrict__ Qb, const u16* __restrict__ Kh, const u16* __restrict__ Vh, int seq, f32x16* o, float* rli) {
;     ...
;     SBAR(); qkt(pB0, pB1, K_lds + b0 * AT_SHM_K, qr, r32, hi);
;     finishSM(pA0, pA1, alA, l_reg, pa0, pa1, pa2, pa3); SBAR();
;     SLOAD(SO, (j + 2) * 64); SBAR();
;     pv_d0(o, vb0 + bm1 * AT_SHM_V, pa0, pa1, pa2, pa3); partialSM(pB0, pB1, m_reg, mnB, alB);
.LBB0_70:
	s_mul_hi_u32 s1, s9, 0xaaaaaaab
	s_lshr_b32 s1, s1, 1
	s_mul_i32 s1, s1, 0xc000
	v_subrev_u32_e32 v190, s1, v184
	s_mul_hi_u32 s1, s51, 0xaaaaaaab
	s_mul_hi_u32 s0, s66, 0xaaaaaaab
	s_lshr_b32 s12, s1, 1
	s_lshr_b32 s0, s0, 1
	s_mul_i32 s1, s12, 0x6000
	s_mul_i32 s15, s0, 0x6000
	v_subrev_u32_e32 v64, s1, v198
	s_mul_i32 s0, s0, 0xc000
	v_subrev_u32_e32 v216, s15, v180
	v_subrev_u32_e32 v164, s1, v200
	v_subrev_u32_e32 v217, s0, v203
	v_subrev_u32_e32 v218, s0, v204
	v_subrev_u32_e32 v191, s1, v209
	v_subrev_u32_e32 v192, s1, v210
	v_add_u32_e32 v141, s14, v181
	v_add_u32_e32 v68, v141, v64
	ds_read_b128 v[64:67], v68
	ds_read_b128 v[68:71], v68 offset:4096
	v_add_u32_e32 v186, v141, v164
	ds_read_b128 v[164:167], v186
	ds_read_b128 v[186:189], v186 offset:4096
	s_waitcnt vmcnt(0)
	v_add_u32_e32 v72, s8, v202
	v_add_u32_e32 v73, v72, v218
	ds_write_b128 v73, v[116:119]
	v_add_u32_e32 v73, v72, v217
	s_add_i32 s13, s14, 0
	ds_write_b128 v73, v[112:115]
	v_add_u32_e32 v73, s13, v216
	ds_write_b128 v73, v[120:123]
	v_exp_f32_e32 v134, v134
	s_waitcnt lgkmcnt(6)
	v_mfma_f32_32x32x16_bf16 v[80:95], v[64:67], v[108:111], v[236:251]
	v_exp_f32_e32 v135, v135
	v_exp_f32_e32 v132, v132
	v_exp_f32_e32 v133, v133
	v_exp_f32_e32 v130, v130
	v_exp_f32_e32 v131, v131
	v_exp_f32_e32 v128, v128
	v_exp_f32_e32 v129, v129
	s_waitcnt lgkmcnt(5)
	v_mfma_f32_32x32x16_bf16 v[64:79], v[68:71], v[108:111], v[236:251]
	v_exp_f32_e32 v126, v126
	v_exp_f32_e32 v127, v127
	v_exp_f32_e32 v124, v124
	v_exp_f32_e32 v125, v125
	s_waitcnt lgkmcnt(4)
	v_mfma_f32_32x32x16_bf16 v[80:95], v[164:167], v[104:107], v[80:95]
	s_waitcnt lgkmcnt(3)
	v_mfma_f32_32x32x16_bf16 v[64:79], v[186:189], v[104:107], v[64:79]
	v_add_u32_e32 v186, v141, v191
	ds_read_b128 v[164:167], v186
	ds_read_b128 v[186:189], v186 offset:4096
	s_waitcnt lgkmcnt(1)
	v_mfma_f32_32x32x16_bf16 v[80:95], v[164:167], v[100:103], v[80:95]
	s_waitcnt lgkmcnt(0)
	v_mfma_f32_32x32x16_bf16 v[64:79], v[186:189], v[100:103], v[64:79]
	v_add_u32_e32 v186, v141, v192
	ds_read_b128 v[164:167], v186
	ds_read_b128 v[186:189], v186 offset:4096
	s_waitcnt lgkmcnt(1)
	v_mfma_f32_32x32x16_bf16 v[80:95], v[164:167], v[96:99], v[80:95]
	v_exp_f32_e32 v166, v136
	v_add_f32_e32 v136, v160, v150
	v_add_f32_e32 v136, v151, v136
	v_add_f32_e32 v136, v161, v136
	v_add_f32_e32 v136, v158, v136
	v_add_f32_e32 v136, v214, v136
	v_add_f32_e32 v136, v159, v136
	v_add_f32_e32 v136, v215, v136
	v_add_f32_e32 v136, v142, v136
	v_add_f32_e32 v136, v146, v136
	v_add_f32_e32 v136, v143, v136
	v_add_f32_e32 v136, v147, v136
	v_exp_f32_e32 v164, v138
	v_add_f32_e32 v136, v144, v136
	v_exp_f32_e32 v165, v139
	v_add_f32_e32 v136, v148, v136
	v_add_f32_e32 v136, v145, v136
	v_exp_f32_e32 v167, v137
	v_add_f32_e32 v136, v149, v136
	v_add_f32_e32 v136, v164, v136
	v_add_f32_e32 v136, v165, v136
	v_add_f32_e32 v136, v166, v136
	v_add_f32_e32 v136, v167, v136
	v_add_f32_e32 v136, v134, v136
	v_add_f32_e32 v136, v135, v136
	v_add_f32_e32 v136, v132, v136
	v_add_f32_e32 v136, v133, v136
	v_add_f32_e32 v136, v130, v136
	v_add_f32_e32 v136, v131, v136
	s_waitcnt lgkmcnt(0)
	v_mfma_f32_32x32x16_bf16 v[64:79], v[186:189], v[96:99], v[64:79]
	v_add_f32_e32 v136, v128, v136
	v_add_f32_e32 v136, v129, v136
	v_add_f32_e32 v136, v126, v136
	v_add_f32_e32 v136, v127, v136
	v_add_f32_e32 v136, v124, v136
	v_add_f32_e32 v211, v125, v136
	v_mov_b32_e32 v212, v211
	v_cvt_pk_bf16_f32 v136, v150, v160
	v_cvt_pk_bf16_f32 v138, v158, v214
	s_nop 1
	v_permlane32_swap_b32_e32 v211, v212
	v_cvt_pk_bf16_f32 v137, v151, v161
	v_cvt_pk_bf16_f32 v139, v159, v215
	v_permlane32_swap_b32_e32 v136, v138
	v_cvt_pk_bf16_f32 v142, v142, v146
	v_cvt_pk_bf16_f32 v143, v143, v147
	v_cvt_pk_bf16_f32 v144, v144, v148
	v_cvt_pk_bf16_f32 v145, v145, v149
	v_cvt_pk_bf16_f32 v146, v164, v165
	v_cvt_pk_bf16_f32 v147, v166, v167
	v_cvt_pk_bf16_f32 v148, v134, v135
	v_cvt_pk_bf16_f32 v149, v132, v133
	v_cvt_pk_bf16_f32 v164, v130, v131
	v_cvt_pk_bf16_f32 v165, v128, v129
	v_cvt_pk_bf16_f32 v166, v126, v127
	v_cvt_pk_bf16_f32 v167, v124, v125
	v_permlane32_swap_b32_e32 v137, v139
	v_permlane32_swap_b32_e32 v142, v144
	v_permlane32_swap_b32_e32 v143, v145
	v_permlane32_swap_b32_e32 v146, v148
	v_permlane32_swap_b32_e32 v147, v149
	v_permlane32_swap_b32_e32 v164, v166
	v_permlane32_swap_b32_e32 v165, v167
	v_lshl_add_u64 v[158:159], v[156:157], 0, s[82:83]
	v_add_co_u32_e32 v124, vcc, s94, v158
	v_lshl_add_u64 v[160:161], v[154:155], 0, s[82:83]
	s_nop 0
	v_addc_co_u32_e32 v125, vcc, 0, v159, vcc
	v_add_co_u32_e32 v128, vcc, s95, v158
	s_mov_b32 s0, 0x18606000
	s_nop 0
	v_addc_co_u32_e32 v129, vcc, 0, v159, vcc
	v_add_co_u32_e32 v132, vcc, s0, v160
	global_load_dwordx4 v[124:127], v[124:125], off
	s_nop 0
	global_load_dwordx4 v[128:131], v[128:129], off
	v_addc_co_u32_e32 v133, vcc, 0, v161, vcc
	global_load_dwordx4 v[132:135], v[132:133], off
	v_add_u32_e32 v150, s8, v190
	ds_read_b64_tr_b16 v[186:187], v150 offset:0
	ds_read_b64_tr_b16 v[188:189], v150 offset:0x800
	ds_read_b64_tr_b16 v[190:191], v150 offset:0x1000
	ds_read_b64_tr_b16 v[192:193], v150 offset:0x1800
	ds_read_b64_tr_b16 v[220:221], v150 offset:0x2000
	ds_read_b64_tr_b16 v[222:223], v150 offset:0x2800
	ds_read_b64_tr_b16 v[224:225], v150 offset:0x3000
	ds_read_b64_tr_b16 v[226:227], v150 offset:0x3800
	s_waitcnt lgkmcnt(0)
; DEV void partialSM(f32x16& p0, f32x16& p1, float& m_reg, float& mn, float& alpha) {
;   constexpr float C = AT_SCALE * 1.4426950408889634f;
;   float pmax = p0[0];
; #pragma unroll
;   for (int r = 1; r < 16; ++r) pmax = fmaxf(pmax, p0[r]);
; #pragma unroll
;   for (int r = 0; r < 16; ++r) pmax = fmaxf(pmax, p1[r]);
;   { auto rr = __builtin_amdgcn_permlane32_swap(__float_as_uint(pmax), __float_as_uint(pmax), false, false);
;     pmax = fmaxf(__uint_as_float(rr[0]), __uint_as_float(rr[1])); }
;   if (__builtin_expect(__all(pmax - m_reg <= AT_THR / AT_SCALE), 1)) { mn = m_reg; alpha = 1.f; }
;   else { mn = fmaxf(m_reg, pmax); alpha = __builtin_amdgcn_exp2f((m_reg - mn) * C); m_reg = mn; }
; DEV void pv_d0(f32x16* o, int vb, bf16x8 pa0, bf16x8 pa1, bf16x8 pa2, bf16x8 pa3) {
;   pv_one<0>(o[0], vb, pa0, pa1, pa2, pa3); pv_one<1>(o[1], vb, pa0, pa1, pa2, pa3); pv_one<2>(o[2], vb, pa0, pa1, pa2, pa3); pv_one<3>(o[3], vb, pa0, pa1, pa2, pa3);
	s_nop 0
	v_mfma_f32_32x32x16_bf16 v[0:15], v[136:139], v[186:189], v[0:15]
	ds_read_b64_tr_b16 v[186:187], v150 offset:0x200
	ds_read_b64_tr_b16 v[188:189], v150 offset:0xa00
	v_mfma_f32_32x32x16_bf16 v[0:15], v[142:145], v[190:193], v[0:15]
	ds_read_b64_tr_b16 v[190:191], v150 offset:0x1200
	ds_read_b64_tr_b16 v[192:193], v150 offset:0x1a00
	v_mfma_f32_32x32x16_bf16 v[0:15], v[146:149], v[220:223], v[0:15]
	ds_read_b64_tr_b16 v[220:221], v150 offset:0x2200
	ds_read_b64_tr_b16 v[222:223], v150 offset:0x2a00
	v_mfma_f32_32x32x16_bf16 v[0:15], v[164:167], v[224:227], v[0:15]
	ds_read_b64_tr_b16 v[224:225], v150 offset:0x3200
	ds_read_b64_tr_b16 v[226:227], v150 offset:0x3a00
	s_waitcnt lgkmcnt(0)
	v_mfma_f32_32x32x16_bf16 v[48:63], v[136:139], v[186:189], v[48:63]
	ds_read_b64_tr_b16 v[186:187], v150 offset:0x400
	ds_read_b64_tr_b16 v[188:189], v150 offset:0xc00
	v_mfma_f32_32x32x16_bf16 v[48:63], v[142:145], v[190:193], v[48:63]
	ds_read_b64_tr_b16 v[190:191], v150 offset:0x1400
	ds_read_b64_tr_b16 v[192:193], v150 offset:0x1c00
	v_mfma_f32_32x32x16_bf16 v[48:63], v[146:149], v[220:223], v[48:63]
	ds_read_b64_tr_b16 v[220:221], v150 offset:0x2400
	ds_read_b64_tr_b16 v[222:223], v150 offset:0x2c00
	v_mfma_f32_32x32x16_bf16 v[48:63], v[164:167], v[224:227], v[48:63]
	ds_read_b64_tr_b16 v[224:225], v150 offset:0x3400
	ds_read_b64_tr_b16 v[226:227], v150 offset:0x3c00
	s_waitcnt lgkmcnt(0)
	v_mfma_f32_32x32x16_bf16 v[32:47], v[136:139], v[186:189], v[32:47]
	ds_read_b64_tr_b16 v[186:187], v150 offset:0x600
	ds_read_b64_tr_b16 v[188:189], v150 offset:0xe00
	v_mfma_f32_32x32x16_bf16 v[32:47], v[142:145], v[190:193], v[32:47]
	ds_read_b64_tr_b16 v[190:191], v150 offset:0x1600
	ds_read_b64_tr_b16 v[192:193], v150 offset:0x1e00
	v_mfma_f32_32x32x16_bf16 v[32:47], v[146:149], v[220:223], v[32:47]
	ds_read_b64_tr_b16 v[220:221], v150 offset:0x2600
	ds_read_b64_tr_b16 v[222:223], v150 offset:0x2e00
	v_mfma_f32_32x32x16_bf16 v[32:47], v[164:167], v[224:227], v[32:47]
	ds_read_b64_tr_b16 v[224:225], v150 offset:0x3600
	ds_read_b64_tr_b16 v[226:227], v150 offset:0x3e00
	s_waitcnt lgkmcnt(0)
	v_mfma_f32_32x32x16_bf16 v[16:31], v[136:139], v[186:189], v[16:31]
	v_max_f32_e32 v136, v80, v81
	v_max3_f32 v137, v64, v65, v66
	v_max3_f32 v136, v136, v82, v83
	v_max3_f32 v137, v137, v67, v68
	v_max3_f32 v136, v136, v84, v85
	v_max3_f32 v137, v137, v69, v70
	v_max3_f32 v136, v136, v86, v87
	v_max3_f32 v137, v137, v71, v72
	v_mfma_f32_32x32x16_bf16 v[16:31], v[142:145], v[190:193], v[16:31]
	v_max3_f32 v136, v136, v88, v89
	v_max3_f32 v137, v137, v73, v74
	v_max3_f32 v136, v136, v90, v91
	v_max3_f32 v137, v137, v75, v76
	v_max3_f32 v136, v136, v92, v93
	v_max3_f32 v137, v137, v77, v78
	v_max3_f32 v136, v136, v94, v95
	v_max3_f32 v136, v136, v137, v79
	v_mfma_f32_32x32x16_bf16 v[16:31], v[146:149], v[220:223], v[16:31]
	v_mov_b32_e32 v137, v136
	s_nop 1
	v_permlane32_swap_b32_e32 v136, v137
	v_max_f32_e32 v136, v136, v137
	v_cmp_ge_f32_e32 vcc, s18, v136
	v_mfma_f32_32x32x16_bf16 v[16:31], v[164:167], v[224:227], v[16:31]
	s_cmp_eq_u64 vcc, exec
	s_cselect_b64 s[0:1], -1, 0
	s_cbranch_scc1 .Lattn_fast1
	v_max_f32_e32 v136, 0, v136
	v_exp_f32_e64 v137, -v136

; #define SBAR() __builtin_amdgcn_sched_barrier(0)
; #define SLOAD(i, k0) do { sr_[i].vs0 = *reinterpret_cast<const bf16x8*>(&Vh[(size_t)((k0) + sr) * 128 + sc]); sr_[i].vs1 = *reinterpret_cast<const bf16x8*>(&Vh[(size_t)((k0) + 32 + sr) * 128 + sc]); \
;     sr_[i].ks0 = *reinterpret_cast<const bf16x8*>(&Kh[(size_t)((k0) + kr) * 64 + kc]); } while (0)
; DEV void partialSM(f32x16& p0, f32x16& p1, float& m_reg, float& mn, float& alpha) {
;   constexpr float C = AT_SCALE * 1.4426950408889634f;
;   float pmax = p0[0];
; #pragma unroll
;   for (int r = 1; r < 16; ++r) pmax = fmaxf(pmax, p0[r]);
; #pragma unroll
;   for (int r = 0; r < 16; ++r) pmax = fmaxf(pmax, p1[r]);
;   { auto rr = __builtin_amdgcn_permlane32_swap(__float_as_uint(pmax), __float_as_uint(pmax), false, false);
;     pmax = fmaxf(__uint_as_float(rr[0]), __uint_as_float(rr[1])); }
;   if (__builtin_expect(__all(pmax - m_reg <= AT_THR / AT_SCALE), 1)) { mn = m_reg; alpha = 1.f; }
;   else { mn = fmaxf(m_reg, pmax); alpha = __builtin_amdgcn_exp2f((m_reg - mn) * C); m_reg = mn; }
; DEV void attn_pass(const u16* __restrict__ Qb, const u16* __restrict__ Kh, const u16* __restrict__ Vh, int seq, f32x16* o, float* rli) {
;     ...
;     if (j + 3 < NT) SLOAD(SE, (j + 3) * 64); SBAR();
;     pv_d0(o, vb0 + b0 * AT_SHM_V, pa0, pa1, pa2, pa3); partialSM(pA0, pA1, m_reg, mnA, alA);
.LBB0_76:
	s_mul_hi_u32 s0, s50, 0xaaaaaaab
	s_lshr_b32 s0, s0, 1
	s_mul_i32 s1, s0, 0x6000
	s_mul_i32 s0, s0, 0xc000
	s_mul_i32 s12, s12, 0xc000
	v_subrev_u32_e32 v158, s12, v208
	v_add_u32_e32 v219, s8, v158
	ds_read_b64_tr_b16 v[158:159], v219 offset:0
	ds_read_b64_tr_b16 v[160:161], v219 offset:0x800
	ds_read_b64_tr_b16 v[164:165], v219 offset:0x1000
	ds_read_b64_tr_b16 v[166:167], v219 offset:0x1800
	ds_read_b64_tr_b16 v[186:187], v219 offset:0x2000
	ds_read_b64_tr_b16 v[188:189], v219 offset:0x2800
	ds_read_b64_tr_b16 v[190:191], v219 offset:0x3000
	ds_read_b64_tr_b16 v[192:193], v219 offset:0x3800
	s_waitcnt lgkmcnt(0)
	s_nop 0
	v_mfma_f32_32x32x16_bf16 v[0:15], v[136:139], v[158:161], v[0:15]
	ds_read_b64_tr_b16 v[158:159], v219 offset:0x200
	ds_read_b64_tr_b16 v[160:161], v219 offset:0xa00
	v_mfma_f32_32x32x16_bf16 v[0:15], v[140:143], v[164:167], v[0:15]
	ds_read_b64_tr_b16 v[164:165], v219 offset:0x1200
	ds_read_b64_tr_b16 v[166:167], v219 offset:0x1a00
	v_mfma_f32_32x32x16_bf16 v[0:15], v[144:147], v[186:189], v[0:15]
	ds_read_b64_tr_b16 v[186:187], v219 offset:0x2200
	ds_read_b64_tr_b16 v[188:189], v219 offset:0x2a00
	v_mfma_f32_32x32x16_bf16 v[0:15], v[148:151], v[190:193], v[0:15]
	ds_read_b64_tr_b16 v[190:191], v219 offset:0x3200
	ds_read_b64_tr_b16 v[192:193], v219 offset:0x3a00
	s_waitcnt lgkmcnt(0)
	v_mfma_f32_32x32x16_bf16 v[48:63], v[136:139], v[158:161], v[48:63]
	ds_read_b64_tr_b16 v[158:159], v219 offset:0x400
	ds_read_b64_tr_b16 v[160:161], v219 offset:0xc00
	v_mfma_f32_32x32x16_bf16 v[48:63], v[140:143], v[164:167], v[48:63]
	ds_read_b64_tr_b16 v[164:165], v219 offset:0x1400
	ds_read_b64_tr_b16 v[166:167], v219 offset:0x1c00
	v_mfma_f32_32x32x16_bf16 v[48:63], v[144:147], v[186:189], v[48:63]
	ds_read_b64_tr_b16 v[186:187], v219 offset:0x2400
	ds_read_b64_tr_b16 v[188:189], v219 offset:0x2c00
	v_mfma_f32_32x32x16_bf16 v[48:63], v[148:151], v[190:193], v[48:63]
	ds_read_b64_tr_b16 v[190:191], v219 offset:0x3400
	ds_read_b64_tr_b16 v[192:193], v219 offset:0x3c00
	s_waitcnt lgkmcnt(0)
	v_mfma_f32_32x32x16_bf16 v[32:47], v[136:139], v[158:161], v[32:47]
	ds_read_b64_tr_b16 v[158:159], v219 offset:0x600
	ds_read_b64_tr_b16 v[160:161], v219 offset:0xe00
	v_mfma_f32_32x32x16_bf16 v[32:47], v[140:143], v[164:167], v[32:47]
	ds_read_b64_tr_b16 v[164:165], v219 offset:0x1600
	ds_read_b64_tr_b16 v[166:167], v219 offset:0x1e00
	v_mfma_f32_32x32x16_bf16 v[32:47], v[144:147], v[186:189], v[32:47]
	ds_read_b64_tr_b16 v[186:187], v219 offset:0x2600
	ds_read_b64_tr_b16 v[188:189], v219 offset:0x2e00
	v_mfma_f32_32x32x16_bf16 v[32:47], v[148:151], v[190:193], v[32:47]
	ds_read_b64_tr_b16 v[190:191], v219 offset:0x3600
	ds_read_b64_tr_b16 v[192:193], v219 offset:0x3e00
	s_waitcnt lgkmcnt(0)
	v_mfma_f32_32x32x16_bf16 v[16:31], v[136:139], v[158:161], v[16:31]
	v_max_f32_e32 v136, v80, v81
	v_max3_f32 v137, v64, v65, v66
	v_max3_f32 v136, v136, v82, v83
	v_max3_f32 v137, v137, v67, v68
	v_max3_f32 v136, v136, v84, v85
	v_max3_f32 v137, v137, v69, v70
	v_max3_f32 v136, v136, v86, v87
	v_max3_f32 v137, v137, v71, v72
	v_mfma_f32_32x32x16_bf16 v[16:31], v[140:143], v[164:167], v[16:31]
	v_max3_f32 v136, v136, v88, v89
	v_max3_f32 v137, v137, v73, v74
	v_max3_f32 v136, v136, v90, v91
	v_max3_f32 v137, v137, v75, v76
	v_max3_f32 v136, v136, v92, v93
	v_max3_f32 v137, v137, v77, v78
	v_max3_f32 v136, v136, v94, v95
	v_max3_f32 v136, v136, v137, v79
	v_mfma_f32_32x32x16_bf16 v[16:31], v[144:147], v[186:189], v[16:31]
	v_mov_b32_e32 v137, v136
	s_nop 1
	v_permlane32_swap_b32_e32 v136, v137
	v_max_f32_e32 v136, v136, v137
	v_cmp_ge_f32_e32 vcc, s18, v136
	v_mfma_f32_32x32x16_bf16 v[16:31], v[148:151], v[190:193], v[16:31]
	s_cmp_eq_u64 vcc, exec
	s_cselect_b64 s[0:1], -1, 0
	s_cbranch_scc1 .Lattn_fast2
	v_max_f32_e32 v136, 0, v136
	v_exp_f32_e64 v137, -v136
	s_nop 0

; #define SBAR() __builtin_amdgcn_sched_barrier(0)
; #define SLOAD(i, k0) do { sr_[i].vs0 = *reinterpret_cast<const bf16x8*>(&Vh[(size_t)((k0) + sr) * 128 + sc]); sr_[i].vs1 = *reinterpret_cast<const bf16x8*>(&Vh[(size_t)((k0) + 32 + sr) * 128 + sc]); \
;     sr_[i].ks0 = *reinterpret_cast<const bf16x8*>(&Kh[(size_t)((k0) + kr) * 64 + kc]); } while (0)
; DEV void finishSM(f32x16& p0, f32x16& p1, float alpha, float& l_reg, bf16x8& pa0, bf16x8& pa1, bf16x8& pa2, bf16x8& pa3) {
; #pragma unroll
;   for (int r = 0; r < 16; ++r) p1[r] = __builtin_amdgcn_exp2f(p1[r]);
;   float ps = 0;
; #pragma unroll
;   for (int r = 0; r < 16; ++r) ps += p0[r];
; #pragma unroll
;   for (int r = 0; r < 16; ++r) ps += p1[r];
;   { auto rr = __builtin_amdgcn_permlane32_swap(__float_as_uint(ps), __float_as_uint(ps), false, false);
;     ps = __uint_as_float(rr[0]) + __uint_as_float(rr[1]); }
;   l_reg = l_reg * alpha + ps;
;     ...
;   PK4(p0, 0, pa0); PK4(p0, 8, pa1); PK4(p1, 0, pa2); PK4(p1, 8, pa3);
; DEV void attn_pass(const u16* __restrict__ Qb, const u16* __restrict__ Kh, const u16* __restrict__ Vh, int seq, f32x16* o, float* rli) {
;     ...
;     SBAR(); qkt(pB0, pB1, K_lds + b0 * AT_SHM_K, qr, r32, hi);
;     finishSM(pA0, pA1, alA, l_reg, pa0, pa1, pa2, pa3); SBAR();
;     SLOAD(SO, (j + 2) * 64); SBAR();
;     pv_d0(o, vb0 + bm1 * AT_SHM_V, pa0, pa1, pa2, pa3); partialSM(pB0, pB1, m_reg, mnB, alB);
.LBB0_90:
	s_mul_hi_u32 s1, s9, 0xaaaaaaab
	s_lshr_b32 s1, s1, 1
	s_mul_i32 s1, s1, 0xc000
	v_subrev_u32_e32 v190, s1, v199
	s_mul_hi_u32 s1, s47, 0xaaaaaaab
	s_mul_hi_u32 s0, s46, 0xaaaaaaab
	s_lshr_b32 s12, s1, 1
	s_lshr_b32 s0, s0, 1
	s_mul_i32 s1, s12, 0x6000
	s_mul_i32 s15, s0, 0x6000
	v_subrev_u32_e32 v64, s1, v201
	s_mul_i32 s0, s0, 0xc000
	v_subrev_u32_e32 v219, s15, v183
	v_subrev_u32_e32 v164, s1, v203
	v_subrev_u32_e32 v220, s0, v206
	v_subrev_u32_e32 v221, s0, v207
	v_subrev_u32_e32 v191, s1, v212
	v_subrev_u32_e32 v192, s1, v213
	v_add_u32_e32 v141, s14, v184
	v_add_u32_e32 v68, v141, v64
	ds_read_b128 v[64:67], v68
	ds_read_b128 v[68:71], v68 offset:4096
	v_add_u32_e32 v186, v141, v164
	ds_read_b128 v[164:167], v186
	ds_read_b128 v[186:189], v186 offset:4096
	s_waitcnt vmcnt(0)
	v_add_u32_e32 v72, s8, v205
	v_add_u32_e32 v73, v72, v221
	ds_write_b128 v73, v[116:119]
	v_add_u32_e32 v73, v72, v220
	s_add_i32 s13, s14, 0
	ds_write_b128 v73, v[112:115]
	v_add_u32_e32 v73, s13, v219
	ds_write_b128 v73, v[120:123]
	v_exp_f32_e32 v134, v134
	s_waitcnt lgkmcnt(6)
	v_mfma_f32_32x32x16_bf16 v[80:95], v[64:67], v[108:111], v[236:251]
	v_exp_f32_e32 v135, v135
	v_exp_f32_e32 v132, v132
	v_exp_f32_e32 v133, v133
	v_exp_f32_e32 v130, v130
	v_exp_f32_e32 v131, v131
	v_exp_f32_e32 v128, v128
	v_exp_f32_e32 v129, v129
	s_waitcnt lgkmcnt(5)
	v_mfma_f32_32x32x16_bf16 v[64:79], v[68:71], v[108:111], v[236:251]
	v_exp_f32_e32 v126, v126
	v_exp_f32_e32 v127, v127
	v_exp_f32_e32 v124, v124
	v_exp_f32_e32 v125, v125
	s_waitcnt lgkmcnt(4)
	v_mfma_f32_32x32x16_bf16 v[80:95], v[164:167], v[104:107], v[80:95]
	s_waitcnt lgkmcnt(3)
	v_mfma_f32_32x32x16_bf16 v[64:79], v[186:189], v[104:107], v[64:79]
	v_add_u32_e32 v186, v141, v191
	ds_read_b128 v[164:167], v186
	ds_read_b128 v[186:189], v186 offset:4096
	s_waitcnt lgkmcnt(1)
	v_mfma_f32_32x32x16_bf16 v[80:95], v[164:167], v[100:103], v[80:95]
	s_waitcnt lgkmcnt(0)
	v_mfma_f32_32x32x16_bf16 v[64:79], v[186:189], v[100:103], v[64:79]
	v_add_u32_e32 v186, v141, v192
	ds_read_b128 v[164:167], v186
	ds_read_b128 v[186:189], v186 offset:4096
	s_waitcnt lgkmcnt(1)
	v_mfma_f32_32x32x16_bf16 v[80:95], v[164:167], v[96:99], v[80:95]
	v_exp_f32_e32 v166, v136
	v_add_f32_e32 v136, v170, v150
	v_add_f32_e32 v136, v151, v136
	v_add_f32_e32 v136, v171, v136
	v_add_f32_e32 v136, v168, v136
	v_add_f32_e32 v136, v217, v136
	v_add_f32_e32 v136, v169, v136
	v_add_f32_e32 v136, v218, v136
	v_add_f32_e32 v136, v142, v136
	v_add_f32_e32 v136, v146, v136
	v_add_f32_e32 v136, v143, v136
	v_add_f32_e32 v136, v147, v136
	v_exp_f32_e32 v164, v138
	v_add_f32_e32 v136, v144, v136
	v_exp_f32_e32 v165, v139
	v_add_f32_e32 v136, v148, v136
	v_add_f32_e32 v136, v145, v136
	v_exp_f32_e32 v167, v137
	v_add_f32_e32 v136, v149, v136
	v_add_f32_e32 v136, v164, v136
	v_add_f32_e32 v136, v165, v136
	v_add_f32_e32 v136, v166, v136
	v_add_f32_e32 v136, v167, v136
	v_add_f32_e32 v136, v134, v136
	v_add_f32_e32 v136, v135, v136
	v_add_f32_e32 v136, v132, v136
	v_add_f32_e32 v136, v133, v136
	v_add_f32_e32 v136, v130, v136
	v_add_f32_e32 v136, v131, v136
	s_waitcnt lgkmcnt(0)
	v_mfma_f32_32x32x16_bf16 v[64:79], v[186:189], v[96:99], v[64:79]
	v_add_f32_e32 v136, v128, v136
	v_add_f32_e32 v136, v129, v136
	v_add_f32_e32 v136, v126, v136
	v_add_f32_e32 v136, v127, v136
	v_add_f32_e32 v136, v124, v136
	v_add_f32_e32 v214, v125, v136
	v_mov_b32_e32 v215, v214
	v_cvt_pk_bf16_f32 v136, v150, v170
	v_cvt_pk_bf16_f32 v138, v168, v217
	s_nop 1
	v_permlane32_swap_b32_e32 v214, v215
	v_cvt_pk_bf16_f32 v137, v151, v171
	v_cvt_pk_bf16_f32 v139, v169, v218
	v_permlane32_swap_b32_e32 v136, v138
	v_cvt_pk_bf16_f32 v142, v142, v146
	v_cvt_pk_bf16_f32 v143, v143, v147
	v_cvt_pk_bf16_f32 v144, v144, v148
	v_cvt_pk_bf16_f32 v145, v145, v149
	v_cvt_pk_bf16_f32 v146, v164, v165
	v_cvt_pk_bf16_f32 v147, v166, v167
	v_cvt_pk_bf16_f32 v148, v134, v135
	v_cvt_pk_bf16_f32 v149, v132, v133
	v_cvt_pk_bf16_f32 v164, v130, v131
	v_cvt_pk_bf16_f32 v165, v128, v129
	v_cvt_pk_bf16_f32 v166, v126, v127
	v_cvt_pk_bf16_f32 v167, v124, v125
	v_permlane32_swap_b32_e32 v137, v139
	v_permlane32_swap_b32_e32 v142, v144
	v_permlane32_swap_b32_e32 v143, v145
	v_permlane32_swap_b32_e32 v146, v148
	v_permlane32_swap_b32_e32 v147, v149
	v_permlane32_swap_b32_e32 v164, v166
	v_permlane32_swap_b32_e32 v165, v167
	v_lshl_add_u64 v[168:169], v[160:161], 0, s[82:83]
	v_add_co_u32_e32 v124, vcc, s94, v168
	v_lshl_add_u64 v[170:171], v[158:159], 0, s[82:83]
	s_nop 0
	v_addc_co_u32_e32 v125, vcc, 0, v169, vcc
	v_add_co_u32_e32 v128, vcc, s95, v168
	s_mov_b32 s0, 0x1868e000
	s_nop 0
	v_addc_co_u32_e32 v129, vcc, 0, v169, vcc
	v_add_co_u32_e32 v132, vcc, s0, v170
	global_load_dwordx4 v[124:127], v[124:125], off
	s_nop 0
	global_load_dwordx4 v[128:131], v[128:129], off
	v_addc_co_u32_e32 v133, vcc, 0, v171, vcc
	global_load_dwordx4 v[132:135], v[132:133], off
	v_add_u32_e32 v150, s8, v190
	ds_read_b64_tr_b16 v[186:187], v150 offset:0
	ds_read_b64_tr_b16 v[188:189], v150 offset:0x800
	ds_read_b64_tr_b16 v[190:191], v150 offset:0x1000
	ds_read_b64_tr_b16 v[192:193], v150 offset:0x1800
	ds_read_b64_tr_b16 v[222:223], v150 offset:0x2000
	ds_read_b64_tr_b16 v[224:225], v150 offset:0x2800
	ds_read_b64_tr_b16 v[226:227], v150 offset:0x3000
	ds_read_b64_tr_b16 v[228:229], v150 offset:0x3800
	s_waitcnt lgkmcnt(0)
; DEV void partialSM(f32x16& p0, f32x16& p1, float& m_reg, float& mn, float& alpha) {
;   constexpr float C = AT_SCALE * 1.4426950408889634f;
;   float pmax = p0[0];
; #pragma unroll
;   for (int r = 1; r < 16; ++r) pmax = fmaxf(pmax, p0[r]);
; #pragma unroll
;   for (int r = 0; r < 16; ++r) pmax = fmaxf(pmax, p1[r]);
;   { auto rr = __builtin_amdgcn_permlane32_swap(__float_as_uint(pmax), __float_as_uint(pmax), false, false);
;     pmax = fmaxf(__uint_as_float(rr[0]), __uint_as_float(rr[1])); }
;   if (__builtin_expect(__all(pmax - m_reg <= AT_THR / AT_SCALE), 1)) { mn = m_reg; alpha = 1.f; }
;   else { mn = fmaxf(m_reg, pmax); alpha = __builtin_amdgcn_exp2f((m_reg - mn) * C); m_reg = mn; }
; DEV void pv_d0(f32x16* o, int vb, bf16x8 pa0, bf16x8 pa1, bf16x8 pa2, bf16x8 pa3) {
;   pv_one<0>(o[0], vb, pa0, pa1, pa2, pa3); pv_one<1>(o[1], vb, pa0, pa1, pa2, pa3); pv_one<2>(o[2], vb, pa0, pa1, pa2, pa3); pv_one<3>(o[3], vb, pa0, pa1, pa2, pa3);
	s_nop 0
	v_mfma_f32_32x32x16_bf16 v[0:15], v[136:139], v[186:189], v[0:15]
	ds_read_b64_tr_b16 v[186:187], v150 offset:0x200
	ds_read_b64_tr_b16 v[188:189], v150 offset:0xa00
	v_mfma_f32_32x32x16_bf16 v[0:15], v[142:145], v[190:193], v[0:15]
	ds_read_b64_tr_b16 v[190:191], v150 offset:0x1200
	ds_read_b64_tr_b16 v[192:193], v150 offset:0x1a00
	v_mfma_f32_32x32x16_bf16 v[0:15], v[146:149], v[222:225], v[0:15]
	ds_read_b64_tr_b16 v[222:223], v150 offset:0x2200
	ds_read_b64_tr_b16 v[224:225], v150 offset:0x2a00
	v_mfma_f32_32x32x16_bf16 v[0:15], v[164:167], v[226:229], v[0:15]
	ds_read_b64_tr_b16 v[226:227], v150 offset:0x3200
	ds_read_b64_tr_b16 v[228:229], v150 offset:0x3a00
	s_waitcnt lgkmcnt(0)
	v_mfma_f32_32x32x16_bf16 v[48:63], v[136:139], v[186:189], v[48:63]
	ds_read_b64_tr_b16 v[186:187], v150 offset:0x400
	ds_read_b64_tr_b16 v[188:189], v150 offset:0xc00
	v_mfma_f32_32x32x16_bf16 v[48:63], v[142:145], v[190:193], v[48:63]
	ds_read_b64_tr_b16 v[190:191], v150 offset:0x1400
	ds_read_b64_tr_b16 v[192:193], v150 offset:0x1c00
	v_mfma_f32_32x32x16_bf16 v[48:63], v[146:149], v[222:225], v[48:63]
	ds_read_b64_tr_b16 v[222:223], v150 offset:0x2400
	ds_read_b64_tr_b16 v[224:225], v150 offset:0x2c00
	v_mfma_f32_32x32x16_bf16 v[48:63], v[164:167], v[226:229], v[48:63]
	ds_read_b64_tr_b16 v[226:227], v150 offset:0x3400
	ds_read_b64_tr_b16 v[228:229], v150 offset:0x3c00
	s_waitcnt lgkmcnt(0)
	v_mfma_f32_32x32x16_bf16 v[32:47], v[136:139], v[186:189], v[32:47]
	ds_read_b64_tr_b16 v[186:187], v150 offset:0x600
	ds_read_b64_tr_b16 v[188:189], v150 offset:0xe00
	v_mfma_f32_32x32x16_bf16 v[32:47], v[142:145], v[190:193], v[32:47]
	ds_read_b64_tr_b16 v[190:191], v150 offset:0x1600
	ds_read_b64_tr_b16 v[192:193], v150 offset:0x1e00
	v_mfma_f32_32x32x16_bf16 v[32:47], v[146:149], v[222:225], v[32:47]
	ds_read_b64_tr_b16 v[222:223], v150 offset:0x2600
	ds_read_b64_tr_b16 v[224:225], v150 offset:0x2e00
	v_mfma_f32_32x32x16_bf16 v[32:47], v[164:167], v[226:229], v[32:47]
	ds_read_b64_tr_b16 v[226:227], v150 offset:0x3600
	ds_read_b64_tr_b16 v[228:229], v150 offset:0x3e00
	s_waitcnt lgkmcnt(0)
	v_mfma_f32_32x32x16_bf16 v[16:31], v[136:139], v[186:189], v[16:31]
	v_max_f32_e32 v136, v80, v81
	v_max3_f32 v137, v64, v65, v66
	v_max3_f32 v136, v136, v82, v83
	v_max3_f32 v137, v137, v67, v68
	v_max3_f32 v136, v136, v84, v85
	v_max3_f32 v137, v137, v69, v70
	v_max3_f32 v136, v136, v86, v87
	v_max3_f32 v137, v137, v71, v72
	v_mfma_f32_32x32x16_bf16 v[16:31], v[142:145], v[190:193], v[16:31]
	v_max3_f32 v136, v136, v88, v89
	v_max3_f32 v137, v137, v73, v74
	v_max3_f32 v136, v136, v90, v91
	v_max3_f32 v137, v137, v75, v76
	v_max3_f32 v136, v136, v92, v93
	v_max3_f32 v137, v137, v77, v78
	v_max3_f32 v136, v136, v94, v95
	v_max3_f32 v136, v136, v137, v79
	v_mfma_f32_32x32x16_bf16 v[16:31], v[146:149], v[222:225], v[16:31]
	v_mov_b32_e32 v137, v136
	s_nop 1
	v_permlane32_swap_b32_e32 v136, v137
	v_max_f32_e32 v136, v136, v137
	v_cmp_ge_f32_e32 vcc, s18, v136
	v_mfma_f32_32x32x16_bf16 v[16:31], v[164:167], v[226:229], v[16:31]
	s_cmp_eq_u64 vcc, exec
	s_cselect_b64 s[0:1], -1, 0
	s_cbranch_scc1 .Lattn_fast3
	v_max_f32_e32 v136, 0, v136
	v_exp_f32_e64 v137, -v136

; #define SBAR() __builtin_amdgcn_sched_barrier(0)
; #define SLOAD(i, k0) do { sr_[i].vs0 = *reinterpret_cast<const bf16x8*>(&Vh[(size_t)((k0) + sr) * 128 + sc]); sr_[i].vs1 = *reinterpret_cast<const bf16x8*>(&Vh[(size_t)((k0) + 32 + sr) * 128 + sc]); \
;     sr_[i].ks0 = *reinterpret_cast<const bf16x8*>(&Kh[(size_t)((k0) + kr) * 64 + kc]); } while (0)
; DEV void partialSM(f32x16& p0, f32x16& p1, float& m_reg, float& mn, float& alpha) {
;   constexpr float C = AT_SCALE * 1.4426950408889634f;
;   float pmax = p0[0];
; #pragma unroll
;   for (int r = 1; r < 16; ++r) pmax = fmaxf(pmax, p0[r]);
; #pragma unroll
;   for (int r = 0; r < 16; ++r) pmax = fmaxf(pmax, p1[r]);
;   { auto rr = __builtin_amdgcn_permlane32_swap(__float_as_uint(pmax), __float_as_uint(pmax), false, false);
;     pmax = fmaxf(__uint_as_float(rr[0]), __uint_as_float(rr[1])); }
;   if (__builtin_expect(__all(pmax - m_reg <= AT_THR / AT_SCALE), 1)) { mn = m_reg; alpha = 1.f; }
;   else { mn = fmaxf(m_reg, pmax); alpha = __builtin_amdgcn_exp2f((m_reg - mn) * C); m_reg = mn; }
; DEV void attn_pass(const u16* __restrict__ Qb, const u16* __restrict__ Kh, const u16* __restrict__ Vh, int seq, f32x16* o, float* rli) {
;     ...
;     if (j + 3 < NT) SLOAD(SE, (j + 3) * 64); SBAR();
;     pv_d0(o, vb0 + b0 * AT_SHM_V, pa0, pa1, pa2, pa3); partialSM(pA0, pA1, m_reg, mnA, alA);
.LBB0_96:
	s_mul_hi_u32 s0, s64, 0xaaaaaaab
	s_lshr_b32 s0, s0, 1
	s_mul_i32 s1, s0, 0x6000
	s_mul_i32 s0, s0, 0xc000
	s_mul_i32 s12, s12, 0xc000
	v_subrev_u32_e32 v164, s12, v211
	v_add_u32_e32 v222, s8, v164
	ds_read_b64_tr_b16 v[164:165], v222 offset:0
	ds_read_b64_tr_b16 v[166:167], v222 offset:0x800
	ds_read_b64_tr_b16 v[168:169], v222 offset:0x1000
	ds_read_b64_tr_b16 v[170:171], v222 offset:0x1800
	ds_read_b64_tr_b16 v[186:187], v222 offset:0x2000
	ds_read_b64_tr_b16 v[188:189], v222 offset:0x2800
	ds_read_b64_tr_b16 v[190:191], v222 offset:0x3000
	ds_read_b64_tr_b16 v[192:193], v222 offset:0x3800
	s_waitcnt lgkmcnt(0)
	s_nop 0
	v_mfma_f32_32x32x16_bf16 v[0:15], v[136:139], v[164:167], v[0:15]
	ds_read_b64_tr_b16 v[164:165], v222 offset:0x200
	ds_read_b64_tr_b16 v[166:167], v222 offset:0xa00
	v_mfma_f32_32x32x16_bf16 v[0:15], v[140:143], v[168:171], v[0:15]
	ds_read_b64_tr_b16 v[168:169], v222 offset:0x1200
	ds_read_b64_tr_b16 v[170:171], v222 offset:0x1a00
	v_mfma_f32_32x32x16_bf16 v[0:15], v[144:147], v[186:189], v[0:15]
	ds_read_b64_tr_b16 v[186:187], v222 offset:0x2200
	ds_read_b64_tr_b16 v[188:189], v222 offset:0x2a00
	v_mfma_f32_32x32x16_bf16 v[0:15], v[148:151], v[190:193], v[0:15]
	ds_read_b64_tr_b16 v[190:191], v222 offset:0x3200
	ds_read_b64_tr_b16 v[192:193], v222 offset:0x3a00
	s_waitcnt lgkmcnt(0)
	v_mfma_f32_32x32x16_bf16 v[48:63], v[136:139], v[164:167], v[48:63]
	ds_read_b64_tr_b16 v[164:165], v222 offset:0x400
	ds_read_b64_tr_b16 v[166:167], v222 offset:0xc00
	v_mfma_f32_32x32x16_bf16 v[48:63], v[140:143], v[168:171], v[48:63]
	ds_read_b64_tr_b16 v[168:169], v222 offset:0x1400
	ds_read_b64_tr_b16 v[170:171], v222 offset:0x1c00
	v_mfma_f32_32x32x16_bf16 v[48:63], v[144:147], v[186:189], v[48:63]
	ds_read_b64_tr_b16 v[186:187], v222 offset:0x2400
	ds_read_b64_tr_b16 v[188:189], v222 offset:0x2c00
	v_mfma_f32_32x32x16_bf16 v[48:63], v[148:151], v[190:193], v[48:63]
	ds_read_b64_tr_b16 v[190:191], v222 offset:0x3400
	ds_read_b64_tr_b16 v[192:193], v222 offset:0x3c00
	s_waitcnt lgkmcnt(0)
	v_mfma_f32_32x32x16_bf16 v[32:47], v[136:139], v[164:167], v[32:47]
	ds_read_b64_tr_b16 v[164:165], v222 offset:0x600
	ds_read_b64_tr_b16 v[166:167], v222 offset:0xe00
	v_mfma_f32_32x32x16_bf16 v[32:47], v[140:143], v[168:171], v[32:47]
	ds_read_b64_tr_b16 v[168:169], v222 offset:0x1600
	ds_read_b64_tr_b16 v[170:171], v222 offset:0x1e00
	v_mfma_f32_32x32x16_bf16 v[32:47], v[144:147], v[186:189], v[32:47]
	ds_read_b64_tr_b16 v[186:187], v222 offset:0x2600
	ds_read_b64_tr_b16 v[188:189], v222 offset:0x2e00
	v_mfma_f32_32x32x16_bf16 v[32:47], v[148:151], v[190:193], v[32:47]
	ds_read_b64_tr_b16 v[190:191], v222 offset:0x3600
	ds_read_b64_tr_b16 v[192:193], v222 offset:0x3e00
	s_waitcnt lgkmcnt(0)
	v_mfma_f32_32x32x16_bf16 v[16:31], v[136:139], v[164:167], v[16:31]
	v_max_f32_e32 v136, v80, v81
	v_max3_f32 v137, v64, v65, v66
	v_max3_f32 v136, v136, v82, v83
	v_max3_f32 v137, v137, v67, v68
	v_max3_f32 v136, v136, v84, v85
	v_max3_f32 v137, v137, v69, v70
	v_max3_f32 v136, v136, v86, v87
	v_max3_f32 v137, v137, v71, v72
	v_mfma_f32_32x32x16_bf16 v[16:31], v[140:143], v[168:171], v[16:31]
	v_max3_f32 v136, v136, v88, v89
	v_max3_f32 v137, v137, v73, v74
	v_max3_f32 v136, v136, v90, v91
	v_max3_f32 v137, v137, v75, v76
	v_max3_f32 v136, v136, v92, v93
	v_max3_f32 v137, v137, v77, v78
	v_max3_f32 v136, v136, v94, v95
	v_max3_f32 v136, v136, v137, v79
	v_mfma_f32_32x32x16_bf16 v[16:31], v[144:147], v[186:189], v[16:31]
	v_mov_b32_e32 v137, v136
	s_nop 1
	v_permlane32_swap_b32_e32 v136, v137
	v_max_f32_e32 v136, v136, v137
	v_cmp_ge_f32_e32 vcc, s18, v136
	v_mfma_f32_32x32x16_bf16 v[16:31], v[148:151], v[190:193], v[16:31]
	s_cmp_eq_u64 vcc, exec
	s_cselect_b64 s[0:1], -1, 0
	s_cbranch_scc1 .Lattn_fast4
	v_max_f32_e32 v136, 0, v136
	v_exp_f32_e64 v137, -v136
	s_nop 0
